# indexer: younger half of the workgroup (waves 4-7) alternates user priority 1/0 per sub-tile step so that neither wave of a SIMD pair runs far ahead of the other between tile barriers
# baseline (speedup 1.0000x reference)
; __device__ __forceinline__ void indexer_block16(const bf16_t* __restrict__ Z, const bf16_t* __restrict__ KI, int* __restrict__ SEL, int qb, LAS unsigned char* lds, int wave) {
;     ...
;         const LAS unsigned char* tb = tiles + (i & 1) * 16384 + lane * 16;
;         float sc[4];
; #pragma unroll
;         for (int st = 0; st < 4; ++st) {
;             bf16x8 Bc[4];
; #pragma unroll
;             for (int kk = 0; kk < 4; ++kk) Bc[kk] = *(const LAS bf16x8*)(tb + (st * 4 + kk) * 1024);
;             f32x16 acc = {0.f, 0.f, 0.f, 0.f, 0.f, 0.f, 0.f, 0.f, 0.f, 0.f, 0.f, 0.f, 0.f, 0.f, 0.f, 0.f};
; #pragma unroll
;             for (int kk = 0; kk < 4; ++kk) acc = __builtin_amdgcn_mfma_f32_32x32x16_bf16(Af[kk], Bc[kk], acc, 0, 0, 0);
;             float s0 = 0.f, s1 = 0.f;
; #pragma unroll
;             for (int h = 0; h < 16; h += 2) { const int b0 = __float_as_int(acc[h]), b1 = __float_as_int(acc[h + 1]);
;                 s0 = fmaf(wq[h], __int_as_float(b0 > 0 ? b0 : 0), s0); s1 = fmaf(wq[h + 1], __int_as_float(b1 > 0 ? b1 : 0), s1); }
;             sc[st] = s0 + s1;
;     ...
;             { f32x16 acc2 = {0.f, 0.f, 0.f, 0.f, 0.f, 0.f, 0.f, 0.f, 0.f, 0.f, 0.f, 0.f, 0.f, 0.f, 0.f, 0.f};
; #pragma unroll
;               for (int kk = 0; kk < 4; ++kk) acc2 = __builtin_amdgcn_mfma_f32_32x32x16_bf16(Af[kk], Bc[3 - kk], acc2, 0, 0, 0);
;               float t0 = 0.f, t1 = 0.f;
; #pragma unroll
;               for (int h = 0; h < 16; h += 2) { const int b0 = __float_as_int(acc2[h]), b1 = __float_as_int(acc2[h + 1]);
;                   t0 = fmaf(wq[h], __int_as_float(b0 > 0 ? b0 : 0), t0); t1 = fmaf(wq[h + 1], __int_as_float(b1 > 0 ? b1 : 0), t1); }
;               asm volatile("" :: "v"(t0 + t1)); }
;     ...
;         }
; #pragma unroll
;         for (int st = 0; st < 4; ++st) {
;             const int key = i * 128 + st * 32 + r;
;             const bool pass = (key <= tmine) && (sc[st] > tau);
;             const unsigned long long mk = __builtin_amdgcn_ballot_w64(pass);
;             if (mk != 0ull) {
;                 const unsigned lo = (unsigned)mk, hi = (unsigned)(mk >> 32);
;                 const int pre = half ? __builtin_amdgcn_mbcnt_hi(hi, 0) : __builtin_amdgcn_mbcnt_lo(lo, 0);
;                 const int base = half ? cntB : cntA;
;                 if (pass) { u32x2 o; o.x = __float_as_uint(sc[st]); o.y = (unsigned)key; wbuf[half * 768 + base + pre] = o; }
.Lidx_tile:
	s_bitcmp1_b32 s33, 8
	s_cbranch_scc0 .Lidx_p1
	s_setprio 1
.Lidx_p1:
	ds_read_b128 v[180:183], v219 offset:8192
	ds_read_b128 v[184:187], v219 offset:9216
	s_waitcnt lgkmcnt(2)
	v_mfma_f32_32x32x16_bf16 v[164:179], v[76:79], v[196:199], 0
	ds_read_b128 v[188:191], v219 offset:10240
	ds_read_b128 v[192:195], v219 offset:11264
	v_max_i32_e32 v148, 0, v148
	v_max_i32_e32 v149, 0, v149
	v_fma_f32 v212, v104, v148, 0
	v_fma_f32 v214, v105, v149, 0
	v_max_i32_e32 v150, 0, v150
	v_max_i32_e32 v151, 0, v151
	v_fmac_f32_e32 v212, v106, v150
	v_fmac_f32_e32 v214, v107, v151
	v_max_i32_e32 v152, 0, v152
	v_max_i32_e32 v153, 0, v153
	v_fmac_f32_e32 v212, v108, v152
	v_fmac_f32_e32 v214, v109, v153
	v_mfma_f32_32x32x16_bf16 v[164:179], v[64:67], v[200:203], v[164:179]
	v_max_i32_e32 v154, 0, v154
	v_max_i32_e32 v155, 0, v155
	v_fmac_f32_e32 v212, v110, v154
	v_fmac_f32_e32 v214, v111, v155
	v_max_i32_e32 v156, 0, v156
	v_max_i32_e32 v157, 0, v157
	v_fmac_f32_e32 v212, v112, v156
	v_fmac_f32_e32 v214, v113, v157
	v_max_i32_e32 v158, 0, v158
	v_max_i32_e32 v159, 0, v159
	v_fmac_f32_e32 v212, v114, v158
	v_fmac_f32_e32 v214, v115, v159
	v_mfma_f32_32x32x16_bf16 v[164:179], v[68:71], v[204:207], v[164:179]
	v_max_i32_e32 v160, 0, v160
	v_max_i32_e32 v161, 0, v161
	v_fmac_f32_e32 v212, v116, v160
	v_fmac_f32_e32 v214, v117, v161
	v_max_i32_e32 v162, 0, v162
	v_max_i32_e32 v163, 0, v163
	v_fmac_f32_e32 v212, v118, v162
	v_fmac_f32_e32 v214, v119, v163
	v_add_f32_e32 v212, v212, v214
	v_cmp_gt_f32_e32 vcc, v212, v128
	v_mov_b32_e32 v213, v223
	s_bcnt1_i32_b32 s4, vcc_lo
	s_bcnt1_i32_b32 s5, vcc_hi
	v_mbcnt_lo_u32_b32 v215, vcc_lo, 0
	v_mfma_f32_32x32x16_bf16 v[164:179], v[72:75], v[208:211], v[164:179]
	v_mbcnt_hi_u32_b32 v216, vcc_hi, 0
	v_add_lshl_u32 v215, v215, s74, 3
	v_add_lshl_u32 v216, v216, s75, 3
	v_cndmask_b32_e64 v215, v216, v215, s[6:7]
	v_add_u32_e32 v215, v126, v215
	s_mov_b64 exec, vcc
	ds_write_b64 v215, v[212:213]
	s_mov_b64 exec, -1
	s_add_i32 s74, s74, s4
	s_add_i32 s75, s75, s5
	s_bitcmp1_b32 s33, 8
	s_cbranch_scc0 .Lidx_p2
	s_setprio 0
.Lidx_p2:
	ds_read_b128 v[196:199], v219 offset:12288
	ds_read_b128 v[200:203], v219 offset:13312
	s_waitcnt lgkmcnt(2)
	v_mfma_f32_32x32x16_bf16 v[148:163], v[76:79], v[180:183], 0
	ds_read_b128 v[204:207], v219 offset:14336
	ds_read_b128 v[208:211], v219 offset:15360
	v_max_i32_e32 v164, 0, v164
	v_max_i32_e32 v165, 0, v165
	v_fma_f32 v212, v104, v164, 0
	v_fma_f32 v214, v105, v165, 0
	v_max_i32_e32 v166, 0, v166
	v_max_i32_e32 v167, 0, v167
	v_fmac_f32_e32 v212, v106, v166
	v_fmac_f32_e32 v214, v107, v167
	v_max_i32_e32 v168, 0, v168
	v_max_i32_e32 v169, 0, v169
	v_fmac_f32_e32 v212, v108, v168
	v_fmac_f32_e32 v214, v109, v169
	v_mfma_f32_32x32x16_bf16 v[148:163], v[64:67], v[184:187], v[148:163]
	v_max_i32_e32 v170, 0, v170
	v_max_i32_e32 v171, 0, v171
	v_fmac_f32_e32 v212, v110, v170
	v_fmac_f32_e32 v214, v111, v171
	v_max_i32_e32 v172, 0, v172
	v_max_i32_e32 v173, 0, v173
	v_fmac_f32_e32 v212, v112, v172
	v_fmac_f32_e32 v214, v113, v173
	v_max_i32_e32 v174, 0, v174
	v_max_i32_e32 v175, 0, v175
	v_fmac_f32_e32 v212, v114, v174
	v_fmac_f32_e32 v214, v115, v175
	v_mfma_f32_32x32x16_bf16 v[148:163], v[68:71], v[188:191], v[148:163]
	v_max_i32_e32 v176, 0, v176
	v_max_i32_e32 v177, 0, v177
	v_fmac_f32_e32 v212, v116, v176
	v_fmac_f32_e32 v214, v117, v177
	v_max_i32_e32 v178, 0, v178
	v_max_i32_e32 v179, 0, v179
	v_fmac_f32_e32 v212, v118, v178
	v_fmac_f32_e32 v214, v119, v179
	v_add_f32_e32 v212, v212, v214
	v_cmp_gt_f32_e32 vcc, v212, v128
	v_or_b32_e32 v213, 32, v223
	s_bcnt1_i32_b32 s4, vcc_lo
	s_bcnt1_i32_b32 s5, vcc_hi
	s_add_i32 s12, s74, s4
	s_add_i32 s13, s75, s5
	s_max_i32 s12, s12, s13
	s_cmpk_gt_i32 s12, 0x280
	s_cselect_b32 s12, 1, 0
	v_mov_b32_e32 v217, s12
	s_mov_b64 exec, 1
	ds_write_b32 v218, v217
	s_mov_b64 exec, -1
	v_mfma_f32_32x32x16_bf16 v[148:163], v[72:75], v[192:195], v[148:163]
	v_mbcnt_lo_u32_b32 v215, vcc_lo, 0
	v_mbcnt_hi_u32_b32 v216, vcc_hi, 0
	v_add_lshl_u32 v215, v215, s74, 3
	v_add_lshl_u32 v216, v216, s75, 3
	v_cndmask_b32_e64 v215, v216, v215, s[6:7]
	v_add_u32_e32 v215, v126, v215
	s_mov_b64 exec, vcc
	ds_write_b64 v215, v[212:213]
	s_mov_b64 exec, -1
	s_add_i32 s74, s74, s4
	s_add_i32 s75, s75, s5
	v_xor_b32_e32 v220, 0x4000, v219
	s_waitcnt vmcnt(0) lgkmcnt(0)
	s_barrier
	s_bitcmp1_b32 s33, 8
	s_cbranch_scc0 .Lidx_p3
	s_setprio 1
.Lidx_p3:
	v_mfma_f32_32x32x16_bf16 v[164:179], v[76:79], v[196:199], 0
	ds_read_b32 v217, v224
	ds_read_b128 v[180:183], v220 offset:0
	ds_read_b128 v[184:187], v220 offset:1024
	ds_read_b128 v[188:191], v220 offset:2048
	ds_read_b128 v[192:195], v220 offset:3072
	v_max_i32_e32 v148, 0, v148
	v_max_i32_e32 v149, 0, v149
	v_fma_f32 v226, v104, v148, 0
	v_fma_f32 v228, v105, v149, 0
	v_max_i32_e32 v150, 0, v150
	v_max_i32_e32 v151, 0, v151
	v_mfma_f32_32x32x16_bf16 v[164:179], v[64:67], v[200:203], v[164:179]
	s_add_i32 s16, s95, 2
	s_cmp_ge_i32 s16, s93
	s_cbranch_scc1 .Lidx_nodma
	s_and_b32 s17, s95, 1
	s_lshl_b32 s17, s17, 14
	s_add_i32 s17, s17, s32
	s_mov_b32 m0, s17
	s_nop 0
	global_load_lds_dwordx4 v221, s[100:101]
	s_add_i32 m0, s17, 0x2000
	s_nop 0
	global_load_lds_dwordx4 v222, s[100:101]
	s_add_u32 s100, s100, 0x4000
	s_addc_u32 s101, s101, 0

; __device__ __forceinline__ void indexer_block16(const bf16_t* __restrict__ Z, const bf16_t* __restrict__ KI, int* __restrict__ SEL, int qb, LAS unsigned char* lds, int wave) {
;     ...
;         if (__builtin_amdgcn_ballot_w64(vote != 0) != 0ull) {
;             if (cntA > 256) { float nt; cntA = topk_compact(wbuf, cntA, nt); tau = half ? tau : nt; }
;             if (cntB > 256) { float nt; cntB = topk_compact(wbuf + 768, cntB, nt); tau = half ? nt : tau; }
;     ...
;             if (cntA >= 256) { float nt; cntA = topk_compact(wbuf, cntA, nt); tau = half ? tau : nt; }
;             if (cntB >= 256) { float nt; cntB = topk_compact(wbuf + 768, cntB, nt); tau = half ? nt : tau; }
;     ...
;         }
;     }
.LBB0_571:
	s_bitcmp1_b32 s33, 8
	s_cbranch_scc0 .Lidx_p4
	s_setprio 0
